# rescale fast path also for the leading wave group's second tile; s_cselect of the ballot moved into the rare block; row-max of the second tile as two interleaved v_max3 chains
# baseline (speedup 1.0000x reference)
; __device__ __forceinline__ void partialSM(f32x16& p0, f32x16& p1, float& m_reg, float& mn, float& alpha) {
;   constexpr float C = SCALE * 1.4426950408889634f;
;   float pmax = p0[0];
; #pragma unroll
;   for (int r = 1; r < 16; ++r) pmax = fmaxf(pmax, p0[r]);
; #pragma unroll
;   for (int r = 0; r < 16; ++r) pmax = fmaxf(pmax, p1[r]);
;   { auto rr = __builtin_amdgcn_permlane32_swap(__float_as_uint(pmax), __float_as_uint(pmax), false, false);
;     pmax = fmaxf(__uint_as_float(rr[0]), __uint_as_float(rr[1])); }
;   if (__builtin_expect(__all(pmax - m_reg <= THR / SCALE), 1)) { mn = m_reg; alpha = 1.f; }
;   else { mn = fmaxf(m_reg, pmax); alpha = __builtin_amdgcn_exp2f((m_reg - mn) * C); m_reg = mn; }
.Lback0_b:
	v_max3_f32 v144, v64, v65, v66
	v_max3_f32 v145, v80, v81, v82
	v_max3_f32 v144, v144, v67, v68
	v_max3_f32 v145, v145, v83, v84
	v_max3_f32 v144, v144, v69, v70
	v_max3_f32 v145, v145, v85, v86
	v_max3_f32 v144, v144, v71, v72
	v_max3_f32 v145, v145, v87, v88
	v_max3_f32 v144, v144, v73, v74
	v_max3_f32 v145, v145, v89, v90
	v_max3_f32 v144, v144, v75, v76
	v_max3_f32 v145, v145, v91, v92
	v_max3_f32 v144, v144, v77, v78
	v_max3_f32 v145, v145, v93, v94
	v_max3_f32 v144, v144, v79, v95
	v_max_f32_e32 v144, v144, v145
	v_mov_b32_e32 v145, v144
	s_nop 1
	v_permlane32_swap_b32_e32 v144, v145
	v_max_f32_e32 v144, v144, v145
	v_sub_f32_e32 v145, v144, v220
	v_cmp_ge_f32_e32 vcc, s30, v145
	s_cmp_eq_u64 vcc, exec
	s_waitcnt lgkmcnt(0)
	s_barrier
	v_mov_b32_e32 v222, v76
	v_mov_b32_e32 v223, v77
	v_mov_b32_e32 v76, v90
	v_mov_b32_e32 v77, v91
	v_mov_b32_e32 v226, v72
	v_mov_b32_e32 v227, v73
	v_mov_b32_e32 v224, v74
	v_mov_b32_e32 v225, v75
	v_mov_b32_e32 v74, v92
	v_mov_b32_e32 v75, v93
	v_mov_b32_e32 v73, v94
	v_mov_b32_e32 v72, v95
	s_cbranch_scc0 .Lslow_b0
	v_mov_b32_e32 v221, 1.0

; #define QSTEP(d, A, B, NA, NB) do { if ((d) + 2 < 12) { NA = KLD((d) + 2, 0); NB = KLD((d) + 2, 1); } SBAR(); \
;     p0 = __builtin_amdgcn_mfma_f32_32x32x16_bf16(A, qr[d], p0, 0, 0, 0); p1 = __builtin_amdgcn_mfma_f32_32x32x16_bf16(B, qr[d], p1, 0, 0, 0); SBAR(); } while (0)
; __device__ __forceinline__ void partialSM(f32x16& p0, f32x16& p1, float& m_reg, float& mn, float& alpha) {
;   constexpr float C = SCALE * 1.4426950408889634f;
;   float pmax = p0[0];
; #pragma unroll
;   for (int r = 1; r < 16; ++r) pmax = fmaxf(pmax, p0[r]);
; #pragma unroll
;   for (int r = 0; r < 16; ++r) pmax = fmaxf(pmax, p1[r]);
;   { auto rr = __builtin_amdgcn_permlane32_swap(__float_as_uint(pmax), __float_as_uint(pmax), false, false);
;     pmax = fmaxf(__uint_as_float(rr[0]), __uint_as_float(rr[1])); }
;   if (__builtin_expect(__all(pmax - m_reg <= THR / SCALE), 1)) { mn = m_reg; alpha = 1.f; }
;   else { mn = fmaxf(m_reg, pmax); alpha = __builtin_amdgcn_exp2f((m_reg - mn) * C); m_reg = mn; }
; __device__ __forceinline__ void qkt2(f32x16& p0, f32x16& p1, const char* Ks, const bf16x8* qr, const int* kb4) {
;     ...
;   QSTEP(0, a0, b0, a2, b2); QSTEP(1, a1, b1, a0, b0); QSTEP(2, a2, b2, a1, b1);
;   QSTEP(3, a0, b0, a2, b2); QSTEP(4, a1, b1, a0, b0); QSTEP(5, a2, b2, a1, b1);
;   QSTEP(6, a0, b0, a2, b2); QSTEP(7, a1, b1, a0, b0); QSTEP(8, a2, b2, a1, b1);
;   QSTEP(9, a0, b0, a2, b2); QSTEP(10, a1, b1, a0, b0); QSTEP(11, a2, b2, a1, b1);
.LBB0_447:
	s_waitcnt lgkmcnt(5)
	v_mfma_f32_32x32x16_bf16 v[80:95], v[194:197], v[112:115], v[80:95]
	v_mfma_f32_32x32x16_bf16 v[64:79], v[224:227], v[112:115], v[64:79]
	ds_read_b128 v[194:197], v207 offset:57472
	ds_read_b128 v[224:227], v219 offset:12416
	s_waitcnt lgkmcnt(4)
	v_mfma_f32_32x32x16_bf16 v[80:95], v[228:231], v[116:119], v[80:95]
	v_mfma_f32_32x32x16_bf16 v[64:79], v[232:235], v[116:119], v[64:79]
	ds_read_b128 v[228:231], v210 offset:57600
	ds_read_b128 v[232:235], v216 offset:12544
	s_waitcnt lgkmcnt(4)
	v_mfma_f32_32x32x16_bf16 v[80:95], v[236:239], v[120:123], v[80:95]
	v_mfma_f32_32x32x16_bf16 v[64:79], v[240:243], v[120:123], v[64:79]
	ds_read_b128 v[236:239], v209 offset:57600
	ds_read_b128 v[240:243], v217 offset:12544
	s_waitcnt lgkmcnt(4)
	v_mfma_f32_32x32x16_bf16 v[80:95], v[194:197], v[124:127], v[80:95]
	v_mfma_f32_32x32x16_bf16 v[64:79], v[224:227], v[124:127], v[64:79]
	ds_read_b128 v[194:197], v208 offset:57600
	ds_read_b128 v[224:227], v218 offset:12544
	s_waitcnt lgkmcnt(4)
	v_mfma_f32_32x32x16_bf16 v[80:95], v[228:231], v[132:135], v[80:95]
	v_mfma_f32_32x32x16_bf16 v[64:79], v[232:235], v[132:135], v[64:79]
	ds_read_b128 v[228:231], v207 offset:57600
	ds_read_b128 v[232:235], v219 offset:12544
	s_waitcnt lgkmcnt(4)
	v_mfma_f32_32x32x16_bf16 v[80:95], v[236:239], v[140:143], v[80:95]
	v_mfma_f32_32x32x16_bf16 v[64:79], v[240:243], v[140:143], v[64:79]
	s_waitcnt lgkmcnt(2)
	v_mfma_f32_32x32x16_bf16 v[80:95], v[194:197], v[128:131], v[80:95]
	v_mfma_f32_32x32x16_bf16 v[64:79], v[224:227], v[128:131], v[64:79]
	s_waitcnt lgkmcnt(0)
	v_mfma_f32_32x32x16_bf16 v[80:95], v[228:231], v[136:139], v[80:95]
	v_mfma_f32_32x32x16_bf16 v[64:79], v[232:235], v[136:139], v[64:79]
	s_nop 9
	v_max3_f32 v194, v80, v81, v82
	v_max3_f32 v194, v194, v83, v84
	v_max3_f32 v195, v64, v65, v66
	v_max3_f32 v194, v194, v85, v86
	v_max3_f32 v195, v195, v67, v68
	v_max3_f32 v194, v194, v87, v88
	v_max3_f32 v195, v195, v69, v70
	v_max3_f32 v194, v194, v89, v90
	v_max3_f32 v195, v195, v71, v72
	v_max3_f32 v194, v194, v91, v92
	v_max3_f32 v195, v195, v73, v74
	v_max3_f32 v194, v194, v93, v94
	v_max3_f32 v195, v195, v75, v76
	v_max3_f32 v195, v195, v77, v78
	v_max3_f32 v194, v194, v95, v79
	v_max_f32_e32 v194, v194, v195
	v_mov_b32_e32 v195, v194
	s_nop 1
	v_permlane32_swap_b32_e32 v194, v195
	v_max_f32_e32 v194, v194, v195
	v_sub_f32_e32 v196, v194, v220
	v_cmp_ge_f32_e32 vcc, s30, v196
	s_cmp_eq_u64 vcc, exec
	s_waitcnt lgkmcnt(0)
	s_barrier
	s_cbranch_scc0 .Lslow_b1
	v_mov_b32_e32 v194, 1.0

; __device__ __forceinline__ void partialSM(f32x16& p0, f32x16& p1, float& m_reg, float& mn, float& alpha) {
;     ...
;   if (__builtin_expect(__all(pmax - m_reg <= THR / SCALE), 1)) { mn = m_reg; alpha = 1.f; }
;   else { mn = fmaxf(m_reg, pmax); alpha = __builtin_amdgcn_exp2f((m_reg - mn) * C); m_reg = mn; }
.Lslow_b1:
	s_mov_b64 s[8:9], 0
	v_max_f32_e32 v195, v220, v194
	v_sub_f32_e32 v194, v220, v195
	v_mul_f32_e32 v194, 0x3dd53b94, v194
	v_exp_f32_e32 v194, v194
	s_nop 0
	v_cndmask_b32_e64 v194, v194, 1.0, s[8:9]
	v_cmp_gt_f32_e32 vcc, 1.0, v194
	s_cbranch_vccz .LBB0_451
	s_and_saveexec_b64 s[0:1], s[6:7]
	ds_write_b32 v205, v194 offset:128
	s_or_b64 exec, exec, s[0:1]
	s_waitcnt lgkmcnt(0)
	v_add_u32_e32 v196, s3, v184
	ds_read_b128 v[224:227], v196 offset:224
	ds_read_b128 v[228:231], v196 offset:192
	ds_read_b128 v[232:235], v196 offset:160
	ds_read_b128 v[236:239], v196 offset:128
	s_waitcnt lgkmcnt(3)
	v_pk_mul_f32 v[12:13], v[12:13], v[224:225]
	s_waitcnt lgkmcnt(2)
	v_pk_mul_f32 v[8:9], v[8:9], v[228:229]
	s_waitcnt lgkmcnt(1)
	v_pk_mul_f32 v[4:5], v[4:5], v[232:233]
	v_pk_mul_f32 v[14:15], v[14:15], v[226:227]
	v_pk_mul_f32 v[10:11], v[10:11], v[230:231]
	v_pk_mul_f32 v[6:7], v[6:7], v[234:235]
	s_waitcnt lgkmcnt(0)
	v_pk_mul_f32 v[2:3], v[2:3], v[238:239]
	v_pk_mul_f32 v[0:1], v[0:1], v[236:237]
	v_pk_mul_f32 v[60:61], v[60:61], v[224:225]
	v_pk_mul_f32 v[56:57], v[56:57], v[228:229]
	v_pk_mul_f32 v[52:53], v[52:53], v[232:233]
	v_pk_mul_f32 v[62:63], v[62:63], v[226:227]
	v_pk_mul_f32 v[58:59], v[58:59], v[230:231]
	v_pk_mul_f32 v[54:55], v[54:55], v[234:235]
	v_pk_mul_f32 v[50:51], v[50:51], v[238:239]
	v_pk_mul_f32 v[48:49], v[48:49], v[236:237]
	v_pk_mul_f32 v[44:45], v[44:45], v[224:225]
	v_pk_mul_f32 v[40:41], v[40:41], v[228:229]
	v_pk_mul_f32 v[36:37], v[36:37], v[232:233]
	v_pk_mul_f32 v[46:47], v[46:47], v[226:227]
	v_pk_mul_f32 v[42:43], v[42:43], v[230:231]
	v_pk_mul_f32 v[38:39], v[38:39], v[234:235]
	v_pk_mul_f32 v[34:35], v[34:35], v[238:239]
	v_pk_mul_f32 v[32:33], v[32:33], v[236:237]
	v_pk_mul_f32 v[28:29], v[28:29], v[224:225]
	v_pk_mul_f32 v[24:25], v[24:25], v[228:229]
	v_pk_mul_f32 v[20:21], v[20:21], v[232:233]
	v_pk_mul_f32 v[30:31], v[30:31], v[226:227]
	v_pk_mul_f32 v[26:27], v[26:27], v[230:231]
	v_pk_mul_f32 v[22:23], v[22:23], v[234:235]
	v_pk_mul_f32 v[18:19], v[18:19], v[238:239]
	v_pk_mul_f32 v[16:17], v[16:17], v[236:237]

; __device__ __forceinline__ void partialSM(f32x16& p0, f32x16& p1, float& m_reg, float& mn, float& alpha) {
;     ...
;   if (__builtin_expect(__all(pmax - m_reg <= THR / SCALE), 1)) { mn = m_reg; alpha = 1.f; }
;   else { mn = fmaxf(m_reg, pmax); alpha = __builtin_amdgcn_exp2f((m_reg - mn) * C); m_reg = mn; }
.Lslow_b0:
	s_mov_b64 s[8:9], 0
	v_max_f32_e32 v90, v220, v144
	v_sub_f32_e32 v92, v220, v90
	v_mul_f32_e32 v92, 0x3dd53b94, v92
	v_exp_f32_e32 v92, v92
	s_nop 0
	v_cndmask_b32_e64 v221, v92, 1.0, s[8:9]
	v_cmp_gt_f32_e32 vcc, 1.0, v221
	s_cbranch_vccz .LBB0_445
	s_and_saveexec_b64 s[0:1], s[6:7]
	ds_write_b32 v205, v221 offset:128
	s_or_b64 exec, exec, s[0:1]
	s_waitcnt lgkmcnt(0)
	v_add_u32_e32 v91, s3, v184
	ds_read_b128 v[92:95], v91 offset:224
	ds_read_b128 v[228:231], v91 offset:192
	ds_read_b128 v[232:235], v91 offset:160
	ds_read_b128 v[236:239], v91 offset:128
	s_waitcnt lgkmcnt(3)
	v_pk_mul_f32 v[12:13], v[12:13], v[92:93]
	s_waitcnt lgkmcnt(2)
	v_pk_mul_f32 v[8:9], v[8:9], v[228:229]
	s_waitcnt lgkmcnt(1)
	v_pk_mul_f32 v[4:5], v[4:5], v[232:233]
	v_pk_mul_f32 v[14:15], v[14:15], v[94:95]
	v_pk_mul_f32 v[10:11], v[10:11], v[230:231]
	v_pk_mul_f32 v[6:7], v[6:7], v[234:235]
	s_waitcnt lgkmcnt(0)
	v_pk_mul_f32 v[2:3], v[2:3], v[238:239]
	v_pk_mul_f32 v[0:1], v[0:1], v[236:237]
	v_pk_mul_f32 v[60:61], v[60:61], v[92:93]
	v_pk_mul_f32 v[56:57], v[56:57], v[228:229]
	v_pk_mul_f32 v[52:53], v[52:53], v[232:233]
	v_pk_mul_f32 v[62:63], v[62:63], v[94:95]
	v_pk_mul_f32 v[58:59], v[58:59], v[230:231]
	v_pk_mul_f32 v[54:55], v[54:55], v[234:235]
	v_pk_mul_f32 v[50:51], v[50:51], v[238:239]
	v_pk_mul_f32 v[48:49], v[48:49], v[236:237]
	v_pk_mul_f32 v[44:45], v[44:45], v[92:93]
	v_pk_mul_f32 v[40:41], v[40:41], v[228:229]
	v_pk_mul_f32 v[36:37], v[36:37], v[232:233]
	v_pk_mul_f32 v[46:47], v[46:47], v[94:95]
	v_pk_mul_f32 v[42:43], v[42:43], v[230:231]
	v_pk_mul_f32 v[38:39], v[38:39], v[234:235]
	v_pk_mul_f32 v[34:35], v[34:35], v[238:239]
	v_pk_mul_f32 v[32:33], v[32:33], v[236:237]
	v_pk_mul_f32 v[28:29], v[28:29], v[92:93]
	v_pk_mul_f32 v[24:25], v[24:25], v[228:229]
	v_pk_mul_f32 v[20:21], v[20:21], v[232:233]
	v_pk_mul_f32 v[30:31], v[30:31], v[94:95]
	v_pk_mul_f32 v[26:27], v[26:27], v[230:231]
	v_pk_mul_f32 v[22:23], v[22:23], v[234:235]
	v_pk_mul_f32 v[18:19], v[18:19], v[238:239]
	v_pk_mul_f32 v[16:17], v[16:17], v[236:237]

; __device__ __forceinline__ void partialSM(f32x16& p0, f32x16& p1, float& m_reg, float& mn, float& alpha) {
;   constexpr float C = SCALE * 1.4426950408889634f;
;   float pmax = p0[0];
; #pragma unroll
;   for (int r = 1; r < 16; ++r) pmax = fmaxf(pmax, p0[r]);
; #pragma unroll
;   for (int r = 0; r < 16; ++r) pmax = fmaxf(pmax, p1[r]);
;   { auto rr = __builtin_amdgcn_permlane32_swap(__float_as_uint(pmax), __float_as_uint(pmax), false, false);
;     pmax = fmaxf(__uint_as_float(rr[0]), __uint_as_float(rr[1])); }
;   if (__builtin_expect(__all(pmax - m_reg <= THR / SCALE), 1)) { mn = m_reg; alpha = 1.f; }
;   else { mn = fmaxf(m_reg, pmax); alpha = __builtin_amdgcn_exp2f((m_reg - mn) * C); m_reg = mn; }
;   float mnC = -mn * C;
; #pragma unroll
;   for (int r = 0; r < 16; ++r) p0[r] = fmaf(p0[r], C, mnC);
; #pragma unroll
;   for (int r = 0; r < 16; ++r) p1[r] = fmaf(p1[r], C, mnC);
; #pragma unroll
;   for (int r = 0; r < 16; ++r) p0[r] = __builtin_amdgcn_exp2f(p0[r]);
; }
; __device__ __forceinline__ void finishSM(f32x16& p0, f32x16& p1, float alpha, float& l_reg, bf16x8& pa0, bf16x8& pa1, bf16x8& pa2, bf16x8& pa3) {
; #pragma unroll
;   for (int r = 0; r < 16; ++r) p1[r] = __builtin_amdgcn_exp2f(p1[r]);
;   float ps = 0;
; #pragma unroll
;   for (int r = 0; r < 16; ++r) ps += p0[r];
; #pragma unroll
;   for (int r = 0; r < 16; ++r) ps += p1[r];
;   { auto rr = __builtin_amdgcn_permlane32_swap(__float_as_uint(ps), __float_as_uint(ps), false, false);
;     ps = __uint_as_float(rr[0]) + __uint_as_float(rr[1]); }
;   l_reg = l_reg * alpha + ps;
;     ...
;   PK4(p0, 0, pa0); PK4(p0, 8, pa1); PK4(p1, 0, pa2); PK4(p1, 8, pa3);
.Lback0_a:
	v_max3_f32 v248, v64, v65, v66
	v_max3_f32 v249, v80, v81, v82
	v_max3_f32 v248, v248, v67, v68
	v_max3_f32 v249, v249, v83, v84
	v_max3_f32 v248, v248, v69, v70
	v_max3_f32 v249, v249, v85, v86
	v_max3_f32 v248, v248, v71, v72
	v_max3_f32 v249, v249, v87, v88
	v_max3_f32 v248, v248, v73, v74
	v_max3_f32 v249, v249, v89, v90
	v_max3_f32 v248, v248, v75, v76
	v_max3_f32 v249, v249, v91, v92
	v_max3_f32 v248, v248, v77, v78
	v_max3_f32 v249, v249, v93, v94
	v_max3_f32 v248, v248, v79, v95
	v_max_f32_e32 v248, v248, v249
	v_mov_b32_e32 v249, v248
	s_nop 1
	v_permlane32_swap_b32_e32 v248, v249
	v_max_f32_e32 v248, v248, v249
	v_sub_f32_e32 v249, v248, v178
	v_cmp_ge_f32_e32 vcc, s30, v249
	s_cmp_eq_u64 vcc, exec
	s_waitcnt lgkmcnt(0)
	s_barrier
	s_waitcnt vmcnt(0)
	ds_write_b128 v212, v[144:147] offset:16384
	ds_write_b128 v212, v[148:151] offset:17408
	ds_write_b128 v211, v[152:155] offset:57344
	ds_write_b128 v211, v[156:159] offset:57472
	ds_write_b128 v211, v[160:163] offset:57600
	v_lshl_add_u64 v[170:171], s[52:53], 0, v[166:167]
	v_add_co_u32_e32 v148, vcc, s28, v170
	v_lshl_add_u64 v[168:169], s[52:53], 0, v[164:165]
	s_nop 0
	v_addc_co_u32_e32 v149, vcc, 0, v171, vcc
	v_add_co_u32_e32 v160, vcc, 0x1b330000, v168
	global_load_dwordx4 v[144:147], v[148:149], off offset:256
	s_nop 0
	global_load_dwordx4 v[148:151], v[148:149], off offset:384
	v_addc_co_u32_e32 v161, vcc, 0, v169, vcc
	global_load_dwordx4 v[152:155], v[160:161], off
	global_load_dwordx4 v[156:159], v[160:161], off offset:128
	s_nop 0
	global_load_dwordx4 v[160:163], v[160:161], off offset:256
	v_mov_b32_e32 v180, v76
	v_mov_b32_e32 v181, v77
	v_mov_b32_e32 v76, v90
	v_mov_b32_e32 v77, v91
	v_mov_b32_e32 v186, v72
	v_mov_b32_e32 v187, v73
	v_mov_b32_e32 v182, v74
	v_mov_b32_e32 v183, v75
	v_mov_b32_e32 v74, v92
	v_mov_b32_e32 v75, v93
	v_mov_b32_e32 v73, v94
	v_mov_b32_e32 v72, v95
	s_cbranch_scc0 .Lslow_a0
	v_mov_b32_e32 v179, 1.0
.Lafter_a0:
	v_mul_f32_e32 v90, 0xbdd53b94, v178
	v_fmamk_f32 v64, v64, 0x3dd53b94, v90
	v_fmamk_f32 v65, v65, 0x3dd53b94, v90
	v_exp_f32_e32 v64, v64
	v_fmamk_f32 v66, v66, 0x3dd53b94, v90
	v_exp_f32_e32 v65, v65
	v_fmamk_f32 v67, v67, 0x3dd53b94, v90
	v_exp_f32_e32 v66, v66
	v_fmamk_f32 v68, v68, 0x3dd53b94, v90
	v_fmamk_f32 v73, v73, 0x3dd53b94, v90
	v_exp_f32_e32 v67, v67
	v_fmamk_f32 v69, v69, 0x3dd53b94, v90
	v_fmamk_f32 v92, v187, 0x3dd53b94, v90
	v_exp_f32_e32 v68, v68
	v_exp_f32_e32 v187, v73
	v_add_f32_e32 v73, 0, v64
	v_fmamk_f32 v70, v70, 0x3dd53b94, v90
	v_exp_f32_e32 v69, v69
	v_add_f32_e32 v73, v65, v73
	v_fmamk_f32 v71, v71, 0x3dd53b94, v90
	v_exp_f32_e32 v70, v70
	v_add_f32_e32 v73, v66, v73
	v_fmamk_f32 v91, v186, 0x3dd53b94, v90
	v_exp_f32_e32 v71, v71
	v_add_f32_e32 v73, v67, v73
	v_fmamk_f32 v93, v182, 0x3dd53b94, v90
	v_fmamk_f32 v94, v183, 0x3dd53b94, v90
	v_fmamk_f32 v95, v180, 0x3dd53b94, v90
	v_fmamk_f32 v180, v181, 0x3dd53b94, v90
	v_fmamk_f32 v78, v78, 0x3dd53b94, v90
	v_fmamk_f32 v79, v79, 0x3dd53b94, v90
	v_fmamk_f32 v80, v80, 0x3dd53b94, v90
	v_fmamk_f32 v81, v81, 0x3dd53b94, v90
	v_fmamk_f32 v82, v82, 0x3dd53b94, v90
	v_fmamk_f32 v83, v83, 0x3dd53b94, v90
	v_fmamk_f32 v84, v84, 0x3dd53b94, v90
	v_fmamk_f32 v85, v85, 0x3dd53b94, v90
	v_fmamk_f32 v86, v86, 0x3dd53b94, v90
	v_fmamk_f32 v87, v87, 0x3dd53b94, v90
	v_fmamk_f32 v88, v88, 0x3dd53b94, v90
	v_fmamk_f32 v89, v89, 0x3dd53b94, v90
	v_fmamk_f32 v76, v76, 0x3dd53b94, v90
	v_fmamk_f32 v77, v77, 0x3dd53b94, v90
	v_fmamk_f32 v74, v74, 0x3dd53b94, v90
	v_fmamk_f32 v75, v75, 0x3dd53b94, v90
	v_fmac_f32_e32 v90, 0x3dd53b94, v72
	v_exp_f32_e32 v72, v91
	v_add_f32_e32 v73, v68, v73
	v_exp_f32_e32 v91, v92
	v_add_f32_e32 v73, v69, v73
	v_exp_f32_e32 v92, v93
	v_add_f32_e32 v73, v70, v73
	v_exp_f32_e32 v93, v94
	v_add_f32_e32 v73, v71, v73
	v_exp_f32_e32 v94, v95
	v_add_f32_e32 v73, v72, v73
	v_exp_f32_e32 v95, v180
	v_add_f32_e32 v73, v91, v73
	v_exp_f32_e32 v78, v78
	v_add_f32_e32 v73, v92, v73
	v_exp_f32_e32 v79, v79
	v_add_f32_e32 v73, v93, v73
	v_exp_f32_e32 v80, v80
	v_add_f32_e32 v73, v94, v73
	v_exp_f32_e32 v81, v81
	v_add_f32_e32 v73, v95, v73
	v_exp_f32_e32 v82, v82
	v_add_f32_e32 v73, v78, v73
	v_exp_f32_e32 v83, v83
	v_add_f32_e32 v73, v79, v73
	v_exp_f32_e32 v84, v84
	v_add_f32_e32 v73, v80, v73
	v_exp_f32_e32 v85, v85
	v_add_f32_e32 v73, v81, v73
	v_exp_f32_e32 v86, v86
	v_add_f32_e32 v73, v82, v73
	v_exp_f32_e32 v87, v87
	v_add_f32_e32 v73, v83, v73
	v_exp_f32_e32 v88, v88
	v_add_f32_e32 v73, v84, v73
	v_exp_f32_e32 v89, v89
	v_add_f32_e32 v73, v85, v73
	v_exp_f32_e32 v182, v76
	v_add_f32_e32 v73, v86, v73
	v_exp_f32_e32 v77, v77
	v_add_f32_e32 v73, v87, v73
	v_exp_f32_e32 v183, v74
	v_add_f32_e32 v73, v88, v73
	v_exp_f32_e32 v186, v75
	v_add_f32_e32 v73, v89, v73
	v_add_f32_e32 v73, v182, v73
	v_exp_f32_e32 v90, v90
	v_add_f32_e32 v73, v77, v73
	v_add_f32_e32 v73, v183, v73
	v_add_f32_e32 v73, v186, v73
	v_add_f32_e32 v73, v187, v73
	v_add_f32_e32 v180, v90, v73
	v_mov_b32_e32 v181, v180
	v_cvt_pk_bf16_f32 v64, v64, v65
	v_cvt_pk_bf16_f32 v65, v66, v67
	v_cvt_pk_bf16_f32 v66, v68, v69
	v_cvt_pk_bf16_f32 v67, v70, v71
	v_cvt_pk_bf16_f32 v68, v72, v91
	v_cvt_pk_bf16_f32 v69, v92, v93
	v_cvt_pk_bf16_f32 v70, v94, v95
	v_cvt_pk_bf16_f32 v71, v78, v79
	v_cvt_pk_bf16_f32 v72, v80, v81
	v_cvt_pk_bf16_f32 v73, v82, v83
	v_cvt_pk_bf16_f32 v74, v84, v85
	v_cvt_pk_bf16_f32 v75, v86, v87
	v_cvt_pk_bf16_f32 v76, v88, v89
	v_cvt_pk_bf16_f32 v77, v182, v77
	v_cvt_pk_bf16_f32 v78, v183, v186
	v_cvt_pk_bf16_f32 v79, v187, v90
	s_nop 1
	v_permlane32_swap_b32_e32 v180, v181
	v_permlane32_swap_b32_e32 v64, v66
	v_permlane32_swap_b32_e32 v65, v67
	v_permlane32_swap_b32_e32 v68, v70
	v_permlane32_swap_b32_e32 v69, v71
	v_permlane32_swap_b32_e32 v72, v74
	v_permlane32_swap_b32_e32 v73, v75
	v_permlane32_swap_b32_e32 v76, v78
	v_permlane32_swap_b32_e32 v77, v79
	ds_read_b64_tr_b16 v[80:81], v206 offset:0
	ds_read_b64_tr_b16 v[82:83], v206 offset:0x800
	ds_read_b64_tr_b16 v[84:85], v206 offset:0x1000
	ds_read_b64_tr_b16 v[86:87], v206 offset:0x1800
	ds_read_b64_tr_b16 v[88:89], v206 offset:0x2000
	ds_read_b64_tr_b16 v[90:91], v206 offset:0x2800
	ds_read_b64_tr_b16 v[92:93], v206 offset:0x3000
	ds_read_b64_tr_b16 v[94:95], v206 offset:0x3800
	ds_read_b64_tr_b16 v[186:187], v206 offset:0x200
	ds_read_b64_tr_b16 v[188:189], v206 offset:0xa00
	ds_read_b64_tr_b16 v[190:191], v206 offset:0x1200
	ds_read_b64_tr_b16 v[192:193], v206 offset:0x1a00
	ds_read_b64_tr_b16 v[194:195], v206 offset:0x2200
	ds_read_b64_tr_b16 v[196:197], v206 offset:0x2a00
	ds_read_b64_tr_b16 v[214:215], v206 offset:0x3200
	ds_read_b64_tr_b16 v[216:217], v206 offset:0x3a00
	s_waitcnt lgkmcnt(8)
; __device__ __forceinline__ void partialSM(f32x16& p0, f32x16& p1, float& m_reg, float& mn, float& alpha) {
;   constexpr float C = SCALE * 1.4426950408889634f;
;   float pmax = p0[0];
; #pragma unroll
; __device__ __forceinline__ void qkt2(f32x16& p0, f32x16& p1, const char* Ks, const bf16x8* qr, const int* kb4) {
;     ...
;   p0 = f32x16{}; p1 = f32x16{};
;   bf16x8 a0 = KLD(0, 0), b0 = KLD(0, 1), a1 = KLD(1, 0), b1 = KLD(1, 1), a2, b2;
;     ...
;   QSTEP(0, a0, b0, a2, b2); QSTEP(1, a1, b1, a0, b0); QSTEP(2, a2, b2, a1, b1);
;   QSTEP(3, a0, b0, a2, b2); QSTEP(4, a1, b1, a0, b0); QSTEP(5, a2, b2, a1, b1);
;   QSTEP(6, a0, b0, a2, b2); QSTEP(7, a1, b1, a0, b0); QSTEP(8, a2, b2, a1, b1);
;   QSTEP(9, a0, b0, a2, b2); QSTEP(10, a1, b1, a0, b0); QSTEP(11, a2, b2, a1, b1);
;     ...
; }
; template <int D0> __device__ __forceinline__ void v_issue(VSet& s, int vb) {
;   s.l0 = tr_read<v_rd_off(D0, 0, 0)>(vb); s.h0 = tr_read<v_rd_off(D0, 0, 1)>(vb); s.l1 = tr_read<v_rd_off(D0, 1, 0)>(vb); s.h1 = tr_read<v_rd_off(D0, 1, 1)>(vb);
;   s.l2 = tr_read<v_rd_off(D0, 2, 0)>(vb); s.h2 = tr_read<v_rd_off(D0, 2, 1)>(vb); s.l3 = tr_read<v_rd_off(D0, 3, 0)>(vb); s.h3 = tr_read<v_rd_off(D0, 3, 1)>(vb);
; }
; __device__ __forceinline__ void v_mma(f32x16& od, VSet& s, bf16x8 pa0, bf16x8 pa1, bf16x8 pa2, bf16x8 pa3) {
;   asm volatile("" : "+v"(s.l0), "+v"(s.h0), "+v"(s.l1), "+v"(s.h1), "+v"(s.l2), "+v"(s.h2), "+v"(s.l3), "+v"(s.h3));
;     ...
;   od = __builtin_amdgcn_mfma_f32_32x32x16_bf16(pa0, PK(s.l0, s.h0), od, 0, 0, 0);
;   od = __builtin_amdgcn_mfma_f32_32x32x16_bf16(pa1, PK(s.l1, s.h1), od, 0, 0, 0);
;   od = __builtin_amdgcn_mfma_f32_32x32x16_bf16(pa2, PK(s.l2, s.h2), od, 0, 0, 0);
;   od = __builtin_amdgcn_mfma_f32_32x32x16_bf16(pa3, PK(s.l3, s.h3), od, 0, 0, 0);
;     ...
; }
; __device__ __forceinline__ void pv2(f32x16* o, int vb, bf16x8 pa0, bf16x8 pa1, bf16x8 pa2, bf16x8 pa3) {
;   VSet X, Y;
;   SBAR(); v_issue<0>(X, vb); v_issue<1>(Y, vb);
;   asm volatile("s_waitcnt lgkmcnt(8)" ::: "memory"); SBAR(); v_mma(o[0], X, pa0, pa1, pa2, pa3); SBAR();
;   v_issue<2>(X, vb);
;   asm volatile("s_waitcnt lgkmcnt(8)" ::: "memory"); SBAR(); v_mma(o[1], Y, pa0, pa1, pa2, pa3); SBAR();
;   v_issue<3>(Y, vb);
;   asm volatile("s_waitcnt lgkmcnt(8)" ::: "memory"); SBAR(); v_mma(o[2], X, pa0, pa1, pa2, pa3); SBAR();
;   asm volatile("s_waitcnt lgkmcnt(0)" ::: "memory"); SBAR(); v_mma(o[3], Y, pa0, pa1, pa2, pa3); SBAR();
; }
	s_nop 0
	s_nop 0
	v_mfma_f32_32x32x16_bf16 v[0:15], v[64:67], v[80:83], v[0:15]
	v_mfma_f32_32x32x16_bf16 v[0:15], v[68:71], v[84:87], v[0:15]
	v_mfma_f32_32x32x16_bf16 v[0:15], v[72:75], v[88:91], v[0:15]
	v_mfma_f32_32x32x16_bf16 v[0:15], v[76:79], v[92:95], v[0:15]
	ds_read_b64_tr_b16 v[80:81], v206 offset:0x400
	ds_read_b64_tr_b16 v[82:83], v206 offset:0xc00
	ds_read_b64_tr_b16 v[84:85], v206 offset:0x1400
	ds_read_b64_tr_b16 v[86:87], v206 offset:0x1c00
	ds_read_b64_tr_b16 v[88:89], v206 offset:0x2400
	ds_read_b64_tr_b16 v[90:91], v206 offset:0x2c00
	ds_read_b64_tr_b16 v[92:93], v206 offset:0x3400
	ds_read_b64_tr_b16 v[94:95], v206 offset:0x3c00
	s_waitcnt lgkmcnt(8)
	s_nop 0
	v_mfma_f32_32x32x16_bf16 v[48:63], v[64:67], v[186:189], v[48:63]
	v_mfma_f32_32x32x16_bf16 v[48:63], v[68:71], v[190:193], v[48:63]
	v_mfma_f32_32x32x16_bf16 v[48:63], v[72:75], v[194:197], v[48:63]
	v_mfma_f32_32x32x16_bf16 v[48:63], v[76:79], v[214:217], v[48:63]
	ds_read_b64_tr_b16 v[186:187], v206 offset:0x600
	ds_read_b64_tr_b16 v[188:189], v206 offset:0xe00
	ds_read_b64_tr_b16 v[190:191], v206 offset:0x1600
	ds_read_b64_tr_b16 v[192:193], v206 offset:0x1e00
	ds_read_b64_tr_b16 v[194:195], v206 offset:0x2600
	ds_read_b64_tr_b16 v[196:197], v206 offset:0x2e00
	ds_read_b64_tr_b16 v[214:215], v206 offset:0x3600
	ds_read_b64_tr_b16 v[216:217], v206 offset:0x3e00
	s_waitcnt lgkmcnt(8)
	s_nop 0
	v_mfma_f32_32x32x16_bf16 v[32:47], v[64:67], v[80:83], v[32:47]
	v_mfma_f32_32x32x16_bf16 v[32:47], v[68:71], v[84:87], v[32:47]
	v_mfma_f32_32x32x16_bf16 v[32:47], v[72:75], v[88:91], v[32:47]
	v_mfma_f32_32x32x16_bf16 v[32:47], v[76:79], v[92:95], v[32:47]
	s_waitcnt lgkmcnt(0)
	s_nop 0
	v_mfma_f32_32x32x16_bf16 v[16:31], v[64:67], v[186:189], v[16:31]
	v_mfma_f32_32x32x16_bf16 v[16:31], v[68:71], v[190:193], v[16:31]
	v_mfma_f32_32x32x16_bf16 v[16:31], v[72:75], v[194:197], v[16:31]
	v_mfma_f32_32x32x16_bf16 v[16:31], v[76:79], v[214:217], v[16:31]
	s_waitcnt lgkmcnt(0)
	s_barrier
	ds_read_b128 v[64:67], v174 offset:12288
	ds_read_b128 v[186:189], v175 offset:12288
	ds_read_b128 v[190:193], v209 offset:57344
	ds_read_b128 v[194:197], v208 offset:57344
	ds_read_b128 v[68:71], v210 offset:57344
	ds_read_b128 v[214:217], v176 offset:12288
	s_waitcnt lgkmcnt(1)
	v_mfma_f32_32x32x16_bf16 v[80:95], v[68:71], v[96:99], 0
	v_mfma_f32_32x32x16_bf16 v[64:79], v[64:67], v[96:99], 0
	ds_read_b128 v[218:221], v207 offset:57344
	ds_read_b128 v[222:225], v177 offset:12288
	v_mfma_f32_32x32x16_bf16 v[80:95], v[190:193], v[100:103], v[80:95]
	v_mfma_f32_32x32x16_bf16 v[64:79], v[186:189], v[100:103], v[64:79]
	ds_read_b128 v[186:189], v210 offset:57472
	ds_read_b128 v[190:193], v174 offset:12416
	v_mfma_f32_32x32x16_bf16 v[80:95], v[194:197], v[104:107], v[80:95]
	s_waitcnt lgkmcnt(4)
	v_mfma_f32_32x32x16_bf16 v[64:79], v[214:217], v[104:107], v[64:79]
	ds_read_b128 v[194:197], v209 offset:57472
	ds_read_b128 v[214:217], v175 offset:12416
	s_waitcnt lgkmcnt(4)
	v_mfma_f32_32x32x16_bf16 v[80:95], v[218:221], v[108:111], v[80:95]
	v_mfma_f32_32x32x16_bf16 v[64:79], v[222:225], v[108:111], v[64:79]
	ds_read_b128 v[218:221], v208 offset:57472
	ds_read_b128 v[222:225], v176 offset:12416
	s_waitcnt lgkmcnt(4)
	v_mfma_f32_32x32x16_bf16 v[80:95], v[186:189], v[112:115], v[80:95]
	v_mfma_f32_32x32x16_bf16 v[64:79], v[190:193], v[112:115], v[64:79]
	ds_read_b128 v[186:189], v207 offset:57472
	ds_read_b128 v[190:193], v177 offset:12416
	s_waitcnt lgkmcnt(4)
	v_mfma_f32_32x32x16_bf16 v[80:95], v[194:197], v[116:119], v[80:95]
	v_mfma_f32_32x32x16_bf16 v[64:79], v[214:217], v[116:119], v[64:79]
	ds_read_b128 v[194:197], v210 offset:57600
	ds_read_b128 v[214:217], v174 offset:12544
	s_waitcnt lgkmcnt(4)
	v_mfma_f32_32x32x16_bf16 v[80:95], v[218:221], v[120:123], v[80:95]
	v_mfma_f32_32x32x16_bf16 v[64:79], v[222:225], v[120:123], v[64:79]
	ds_read_b128 v[218:221], v209 offset:57600
	ds_read_b128 v[222:225], v175 offset:12544
	s_waitcnt lgkmcnt(4)
	v_mfma_f32_32x32x16_bf16 v[80:95], v[186:189], v[124:127], v[80:95]
	v_mfma_f32_32x32x16_bf16 v[64:79], v[190:193], v[124:127], v[64:79]
	ds_read_b128 v[186:189], v208 offset:57600
	ds_read_b128 v[190:193], v176 offset:12544
	s_waitcnt lgkmcnt(4)
	v_mfma_f32_32x32x16_bf16 v[80:95], v[194:197], v[132:135], v[80:95]
	v_mfma_f32_32x32x16_bf16 v[64:79], v[214:217], v[132:135], v[64:79]
	ds_read_b128 v[194:197], v207 offset:57600
	ds_read_b128 v[214:217], v177 offset:12544
	s_waitcnt lgkmcnt(4)
	v_mfma_f32_32x32x16_bf16 v[80:95], v[218:221], v[140:143], v[80:95]
	v_mfma_f32_32x32x16_bf16 v[64:79], v[222:225], v[140:143], v[64:79]
	s_waitcnt lgkmcnt(2)
	v_mfma_f32_32x32x16_bf16 v[80:95], v[186:189], v[128:131], v[80:95]
	v_mfma_f32_32x32x16_bf16 v[64:79], v[190:193], v[128:131], v[64:79]
	s_waitcnt lgkmcnt(0)
	v_mfma_f32_32x32x16_bf16 v[80:95], v[194:197], v[136:139], v[80:95]
	v_mfma_f32_32x32x16_bf16 v[64:79], v[214:217], v[136:139], v[64:79]
	s_nop 9
	v_max3_f32 v182, v80, v81, v82
	v_max3_f32 v182, v182, v83, v84
	v_max3_f32 v183, v64, v65, v66
	v_max3_f32 v182, v182, v85, v86
	v_max3_f32 v183, v183, v67, v68
	v_max3_f32 v182, v182, v87, v88
	v_max3_f32 v183, v183, v69, v70
	v_max3_f32 v182, v182, v89, v90
	v_max3_f32 v183, v183, v71, v72
	v_max3_f32 v182, v182, v91, v92
	v_max3_f32 v183, v183, v73, v74
	v_max3_f32 v182, v182, v93, v94
	v_max3_f32 v183, v183, v75, v76
	v_max3_f32 v183, v183, v77, v78
	v_max3_f32 v182, v182, v95, v79
	v_max_f32_e32 v182, v182, v183
	v_mov_b32_e32 v183, v182
	s_nop 1
	v_permlane32_swap_b32_e32 v182, v183
	s_waitcnt lgkmcnt(0)
	s_barrier
	v_max_f32_e32 v182, v182, v183
	s_waitcnt vmcnt(0)
	v_sub_f32_e32 v183, v182, v178
	v_cmp_ge_f32_e64 s[8:9], s30, v183
	s_cmpk_gt_u32 s19, 0xfd
	ds_write_b128 v212, v[144:147]
	ds_write_b128 v212, v[148:151] offset:1024
	ds_write_b128 v211, v[152:155] offset:32768
	ds_write_b128 v211, v[156:159] offset:32896
	ds_write_b128 v211, v[160:163] offset:33024
	s_cbranch_scc1 .LBB0_465
	v_add_co_u32_e32 v148, vcc, 0x28780000, v170
	s_nop 1
	v_addc_co_u32_e32 v149, vcc, 0, v171, vcc
	v_add_co_u32_e32 v160, vcc, 0x1b360000, v168
	global_load_dwordx4 v[144:147], v[148:149], off offset:256
	s_nop 0
	global_load_dwordx4 v[148:151], v[148:149], off offset:384
	v_addc_co_u32_e32 v161, vcc, 0, v169, vcc
	global_load_dwordx4 v[152:155], v[160:161], off
	global_load_dwordx4 v[156:159], v[160:161], off offset:128
	s_nop 0
	global_load_dwordx4 v[160:163], v[160:161], off offset:256
; #define SBAR() __builtin_amdgcn_sched_barrier(0)
; __device__ __forceinline__ void partialSM(f32x16& p0, f32x16& p1, float& m_reg, float& mn, float& alpha) {
;   constexpr float C = SCALE * 1.4426950408889634f;
;   float pmax = p0[0];
; #pragma unroll
;   for (int r = 1; r < 16; ++r) pmax = fmaxf(pmax, p0[r]);
; #pragma unroll
;   for (int r = 0; r < 16; ++r) pmax = fmaxf(pmax, p1[r]);
;   { auto rr = __builtin_amdgcn_permlane32_swap(__float_as_uint(pmax), __float_as_uint(pmax), false, false);
;     pmax = fmaxf(__uint_as_float(rr[0]), __uint_as_float(rr[1])); }
;   if (__builtin_expect(__all(pmax - m_reg <= THR / SCALE), 1)) { mn = m_reg; alpha = 1.f; }
;   else { mn = fmaxf(m_reg, pmax); alpha = __builtin_amdgcn_exp2f((m_reg - mn) * C); m_reg = mn; }
;   float mnC = -mn * C;
; #pragma unroll
;   for (int r = 0; r < 16; ++r) p0[r] = fmaf(p0[r], C, mnC);
; #pragma unroll
;   for (int r = 0; r < 16; ++r) p1[r] = fmaf(p1[r], C, mnC);
; #pragma unroll
;   for (int r = 0; r < 16; ++r) p0[r] = __builtin_amdgcn_exp2f(p0[r]);
; }
; __device__ __forceinline__ void finishSM(f32x16& p0, f32x16& p1, float alpha, float& l_reg, bf16x8& pa0, bf16x8& pa1, bf16x8& pa2, bf16x8& pa3) {
; #pragma unroll
;   for (int r = 0; r < 16; ++r) p1[r] = __builtin_amdgcn_exp2f(p1[r]);
;   float ps = 0;
; #pragma unroll
;   for (int r = 0; r < 16; ++r) ps += p0[r];
; #pragma unroll
;   for (int r = 0; r < 16; ++r) ps += p1[r];
;   { auto rr = __builtin_amdgcn_permlane32_swap(__float_as_uint(ps), __float_as_uint(ps), false, false);
;     ps = __uint_as_float(rr[0]) + __uint_as_float(rr[1]); }
;   l_reg = l_reg * alpha + ps;
;     ...
;   PK4(p0, 0, pa0); PK4(p0, 8, pa1); PK4(p1, 0, pa2); PK4(p1, 8, pa3);
; __device__ __forceinline__ void pv2(f32x16* o, int vb, bf16x8 pa0, bf16x8 pa1, bf16x8 pa2, bf16x8 pa3) {
;   VSet X, Y;
;   SBAR(); v_issue<0>(X, vb); v_issue<1>(Y, vb);
;   asm volatile("s_waitcnt lgkmcnt(8)" ::: "memory"); SBAR(); v_mma(o[0], X, pa0, pa1, pa2, pa3); SBAR();
;   v_issue<2>(X, vb);
;   asm volatile("s_waitcnt lgkmcnt(8)" ::: "memory"); SBAR(); v_mma(o[1], Y, pa0, pa1, pa2, pa3); SBAR();
;   v_issue<3>(Y, vb);
;   asm volatile("s_waitcnt lgkmcnt(8)" ::: "memory"); SBAR(); v_mma(o[2], X, pa0, pa1, pa2, pa3); SBAR();
;   asm volatile("s_waitcnt lgkmcnt(0)" ::: "memory"); SBAR(); v_mma(o[3], Y, pa0, pa1, pa2, pa3); SBAR();
; }
.LBB0_465:
	s_cmp_eq_u64 s[8:9], exec
	s_cbranch_scc0 .Lslow_a1
	v_mov_b32_e32 v168, 1.0
.Lafter_a1:
	v_mul_f32_e32 v169, 0xbdd53b94, v178
	v_fmamk_f32 v80, v80, 0x3dd53b94, v169
	v_fmamk_f32 v81, v81, 0x3dd53b94, v169
	v_fmamk_f32 v82, v82, 0x3dd53b94, v169
	v_fmamk_f32 v83, v83, 0x3dd53b94, v169
	v_fmamk_f32 v84, v84, 0x3dd53b94, v169
	v_fmamk_f32 v85, v85, 0x3dd53b94, v169
	v_fmamk_f32 v86, v86, 0x3dd53b94, v169
	v_fmamk_f32 v87, v87, 0x3dd53b94, v169
	v_fmamk_f32 v88, v88, 0x3dd53b94, v169
	v_fmamk_f32 v89, v89, 0x3dd53b94, v169
	v_fmamk_f32 v90, v90, 0x3dd53b94, v169
	v_fmamk_f32 v91, v91, 0x3dd53b94, v169
	v_fmamk_f32 v92, v92, 0x3dd53b94, v169
	v_fmamk_f32 v93, v93, 0x3dd53b94, v169
	v_fmamk_f32 v94, v94, 0x3dd53b94, v169
	v_fmamk_f32 v95, v95, 0x3dd53b94, v169
	v_fmamk_f32 v64, v64, 0x3dd53b94, v169
	v_fmamk_f32 v65, v65, 0x3dd53b94, v169
	v_fmamk_f32 v66, v66, 0x3dd53b94, v169
	v_fmamk_f32 v67, v67, 0x3dd53b94, v169
	v_fmamk_f32 v68, v68, 0x3dd53b94, v169
	v_fmamk_f32 v69, v69, 0x3dd53b94, v169
	v_fmamk_f32 v70, v70, 0x3dd53b94, v169
	v_fmamk_f32 v71, v71, 0x3dd53b94, v169
	v_fmamk_f32 v72, v72, 0x3dd53b94, v169
	v_fmamk_f32 v73, v73, 0x3dd53b94, v169
	v_fmamk_f32 v74, v74, 0x3dd53b94, v169
	v_fmamk_f32 v75, v75, 0x3dd53b94, v169
	v_fmamk_f32 v76, v76, 0x3dd53b94, v169
	v_fmamk_f32 v77, v77, 0x3dd53b94, v169
	v_fmamk_f32 v78, v78, 0x3dd53b94, v169
	v_fmac_f32_e32 v169, 0x3dd53b94, v79
	v_exp_f32_e32 v79, v80
	v_exp_f32_e32 v80, v81
	v_exp_f32_e32 v81, v82
	v_exp_f32_e32 v82, v83
	v_exp_f32_e32 v83, v84
	v_exp_f32_e32 v84, v85
	v_exp_f32_e32 v85, v86
	v_exp_f32_e32 v86, v87
	v_exp_f32_e32 v87, v88
	v_exp_f32_e32 v88, v89
	v_exp_f32_e32 v89, v90
	v_exp_f32_e32 v90, v91
	v_exp_f32_e32 v91, v92
	v_exp_f32_e32 v92, v93
	v_exp_f32_e32 v93, v94
	v_exp_f32_e32 v94, v95
	v_exp_f32_e32 v95, v64
	v_add_f32_e32 v64, 0, v79
	v_add_f32_e32 v64, v80, v64
	v_add_f32_e32 v64, v81, v64
	v_add_f32_e32 v64, v82, v64
	v_add_f32_e32 v64, v83, v64
	v_add_f32_e32 v64, v84, v64
	v_add_f32_e32 v64, v85, v64
	v_add_f32_e32 v64, v86, v64
	v_add_f32_e32 v64, v87, v64
	v_add_f32_e32 v64, v88, v64
	v_add_f32_e32 v64, v89, v64
	v_add_f32_e32 v64, v90, v64
	v_add_f32_e32 v64, v91, v64
	v_add_f32_e32 v170, v180, v181
	v_exp_f32_e32 v171, v65
	v_add_f32_e32 v64, v92, v64
	v_fmac_f32_e32 v170, v172, v179
	v_exp_f32_e32 v179, v66
	v_add_f32_e32 v64, v93, v64
	v_exp_f32_e32 v180, v67
	v_add_f32_e32 v64, v94, v64
	v_exp_f32_e32 v181, v68
	v_add_f32_e32 v64, v95, v64
	v_exp_f32_e32 v182, v69
	v_add_f32_e32 v64, v171, v64
	v_exp_f32_e32 v183, v70
	v_add_f32_e32 v64, v179, v64
	v_exp_f32_e32 v186, v71
	v_add_f32_e32 v64, v180, v64
	v_exp_f32_e32 v187, v72
	v_add_f32_e32 v64, v181, v64
	v_exp_f32_e32 v188, v73
	v_add_f32_e32 v64, v182, v64
	v_exp_f32_e32 v189, v74
	v_add_f32_e32 v64, v183, v64
	v_exp_f32_e32 v190, v75
	v_add_f32_e32 v64, v186, v64
	v_exp_f32_e32 v191, v76
	v_add_f32_e32 v64, v187, v64
	v_exp_f32_e32 v192, v77
	v_add_f32_e32 v64, v188, v64
	v_exp_f32_e32 v193, v78
	v_add_f32_e32 v64, v189, v64
	v_exp_f32_e32 v169, v169
	v_add_f32_e32 v64, v190, v64
	v_add_f32_e32 v64, v191, v64
	v_add_f32_e32 v64, v192, v64
	v_add_f32_e32 v64, v193, v64
	v_add_f32_e32 v64, v169, v64
	v_mov_b32_e32 v65, v64
	s_nop 1
	v_permlane32_swap_b32_e32 v64, v65
	v_add_f32_e32 v172, v64, v65
	v_fmac_f32_e32 v172, v170, v168
	v_cvt_pk_bf16_f32 v64, v79, v80
	v_cvt_pk_bf16_f32 v65, v81, v82
	v_cvt_pk_bf16_f32 v66, v83, v84
	v_cvt_pk_bf16_f32 v67, v85, v86
	v_cvt_pk_bf16_f32 v68, v87, v88
	v_cvt_pk_bf16_f32 v69, v89, v90
	v_cvt_pk_bf16_f32 v70, v91, v92
	v_cvt_pk_bf16_f32 v71, v93, v94
	v_cvt_pk_bf16_f32 v72, v95, v171
	v_cvt_pk_bf16_f32 v73, v179, v180
	v_cvt_pk_bf16_f32 v74, v181, v182
	v_cvt_pk_bf16_f32 v75, v183, v186
	v_cvt_pk_bf16_f32 v76, v187, v188
	v_cvt_pk_bf16_f32 v77, v189, v190
	v_cvt_pk_bf16_f32 v78, v191, v192
	v_cvt_pk_bf16_f32 v79, v193, v169
	s_nop 0
	v_permlane32_swap_b32_e32 v64, v66
	v_permlane32_swap_b32_e32 v65, v67
	v_permlane32_swap_b32_e32 v68, v70
	v_permlane32_swap_b32_e32 v69, v71
	v_permlane32_swap_b32_e32 v72, v74
	v_permlane32_swap_b32_e32 v73, v75
	v_permlane32_swap_b32_e32 v76, v78
	v_permlane32_swap_b32_e32 v77, v79
	ds_read_b64_tr_b16 v[80:81], v173 offset:0
	ds_read_b64_tr_b16 v[82:83], v173 offset:0x800
	ds_read_b64_tr_b16 v[84:85], v173 offset:0x1000
	ds_read_b64_tr_b16 v[86:87], v173 offset:0x1800
	ds_read_b64_tr_b16 v[88:89], v173 offset:0x2000
	ds_read_b64_tr_b16 v[90:91], v173 offset:0x2800
	ds_read_b64_tr_b16 v[92:93], v173 offset:0x3000
	ds_read_b64_tr_b16 v[94:95], v173 offset:0x3800
	ds_read_b64_tr_b16 v[168:169], v173 offset:0x200
	ds_read_b64_tr_b16 v[170:171], v173 offset:0xa00
	ds_read_b64_tr_b16 v[180:181], v173 offset:0x1200
	ds_read_b64_tr_b16 v[182:183], v173 offset:0x1a00
	ds_read_b64_tr_b16 v[186:187], v173 offset:0x2200
	ds_read_b64_tr_b16 v[188:189], v173 offset:0x2a00
	ds_read_b64_tr_b16 v[190:191], v173 offset:0x3200
	ds_read_b64_tr_b16 v[192:193], v173 offset:0x3a00
	s_waitcnt lgkmcnt(8)
	s_nop 0
	s_nop 0
	v_mfma_f32_32x32x16_bf16 v[0:15], v[64:67], v[80:83], v[0:15]
	v_mfma_f32_32x32x16_bf16 v[0:15], v[68:71], v[84:87], v[0:15]
	v_mfma_f32_32x32x16_bf16 v[0:15], v[72:75], v[88:91], v[0:15]
	v_mfma_f32_32x32x16_bf16 v[0:15], v[76:79], v[92:95], v[0:15]
	ds_read_b64_tr_b16 v[80:81], v173 offset:0x400
	ds_read_b64_tr_b16 v[82:83], v173 offset:0xc00
	ds_read_b64_tr_b16 v[84:85], v173 offset:0x1400
	ds_read_b64_tr_b16 v[86:87], v173 offset:0x1c00
	ds_read_b64_tr_b16 v[88:89], v173 offset:0x2400
	ds_read_b64_tr_b16 v[90:91], v173 offset:0x2c00
	ds_read_b64_tr_b16 v[92:93], v173 offset:0x3400
	ds_read_b64_tr_b16 v[94:95], v173 offset:0x3c00
	s_waitcnt lgkmcnt(8)
	s_nop 0
	v_mfma_f32_32x32x16_bf16 v[48:63], v[64:67], v[168:171], v[48:63]
	v_mfma_f32_32x32x16_bf16 v[48:63], v[68:71], v[180:183], v[48:63]
	v_mfma_f32_32x32x16_bf16 v[48:63], v[72:75], v[186:189], v[48:63]
	v_mfma_f32_32x32x16_bf16 v[48:63], v[76:79], v[190:193], v[48:63]
	ds_read_b64_tr_b16 v[168:169], v173 offset:0x600
	ds_read_b64_tr_b16 v[170:171], v173 offset:0xe00
	ds_read_b64_tr_b16 v[180:181], v173 offset:0x1600
	ds_read_b64_tr_b16 v[182:183], v173 offset:0x1e00
	ds_read_b64_tr_b16 v[186:187], v173 offset:0x2600
	ds_read_b64_tr_b16 v[188:189], v173 offset:0x2e00
	ds_read_b64_tr_b16 v[190:191], v173 offset:0x3600
	ds_read_b64_tr_b16 v[192:193], v173 offset:0x3e00
	s_waitcnt lgkmcnt(8)
	s_nop 0
	v_mfma_f32_32x32x16_bf16 v[32:47], v[64:67], v[80:83], v[32:47]
	v_mfma_f32_32x32x16_bf16 v[32:47], v[68:71], v[84:87], v[32:47]
	v_mfma_f32_32x32x16_bf16 v[32:47], v[72:75], v[88:91], v[32:47]
	v_mfma_f32_32x32x16_bf16 v[32:47], v[76:79], v[92:95], v[32:47]
	s_waitcnt lgkmcnt(0)
	s_nop 0
	v_mfma_f32_32x32x16_bf16 v[16:31], v[64:67], v[168:171], v[16:31]
	v_mfma_f32_32x32x16_bf16 v[16:31], v[68:71], v[180:183], v[16:31]
	v_mfma_f32_32x32x16_bf16 v[16:31], v[72:75], v[186:189], v[16:31]
	v_mfma_f32_32x32x16_bf16 v[16:31], v[76:79], v[190:193], v[16:31]
	s_waitcnt lgkmcnt(0)
	s_barrier
; __device__ __forceinline__ void partialSM(f32x16& p0, f32x16& p1, float& m_reg, float& mn, float& alpha) {
;     ...
;   if (__builtin_expect(__all(pmax - m_reg <= THR / SCALE), 1)) { mn = m_reg; alpha = 1.f; }
;   else { mn = fmaxf(m_reg, pmax); alpha = __builtin_amdgcn_exp2f((m_reg - mn) * C); m_reg = mn; }
	s_add_i32 s0, s19, 2
	s_add_i32 s1, s19, 3
	s_add_i32 s42, s42, -2
	v_lshl_add_u64 v[164:165], v[164:165], 0, s[14:15]
	s_cmpk_gt_u32 s1, 0x100
	v_lshl_add_u64 v[166:167], v[166:167], 0, s[16:17]
	s_cbranch_scc1 .LBB0_471
	s_mov_b32 s19, s0
	s_branch .LBB0_459
.Lslow_a1:
	v_max_f32_e32 v169, v178, v182
	v_sub_f32_e32 v168, v178, v169
	v_mul_f32_e32 v168, 0x3dd53b94, v168
	v_exp_f32_e32 v168, v168
	s_mov_b64 s[8:9], 0
	s_nop 0
	v_cndmask_b32_e64 v168, v168, 1.0, s[8:9]
	v_cmp_gt_f32_e32 vcc, 1.0, v168
	s_cbranch_vccz .LBB0_469
	s_and_saveexec_b64 s[0:1], s[6:7]
	ds_write_b32 v205, v168 offset:128
	s_or_b64 exec, exec, s[0:1]
	s_waitcnt lgkmcnt(0)
	v_add_u32_e32 v170, s3, v184
	ds_read_b128 v[186:189], v170 offset:224
	ds_read_b128 v[190:193], v170 offset:192
	ds_read_b128 v[194:197], v170 offset:160
	ds_read_b128 v[214:217], v170 offset:128
	s_waitcnt lgkmcnt(3)
	v_pk_mul_f32 v[12:13], v[12:13], v[186:187]
	s_waitcnt lgkmcnt(2)
	v_pk_mul_f32 v[8:9], v[8:9], v[190:191]
	s_waitcnt lgkmcnt(1)
	v_pk_mul_f32 v[4:5], v[4:5], v[194:195]
	v_pk_mul_f32 v[14:15], v[14:15], v[188:189]
	v_pk_mul_f32 v[10:11], v[10:11], v[192:193]
	v_pk_mul_f32 v[6:7], v[6:7], v[196:197]
	s_waitcnt lgkmcnt(0)
	v_pk_mul_f32 v[2:3], v[2:3], v[216:217]
	v_pk_mul_f32 v[0:1], v[0:1], v[214:215]
	v_pk_mul_f32 v[60:61], v[60:61], v[186:187]
	v_pk_mul_f32 v[56:57], v[56:57], v[190:191]
	v_pk_mul_f32 v[52:53], v[52:53], v[194:195]
	v_pk_mul_f32 v[62:63], v[62:63], v[188:189]
	v_pk_mul_f32 v[58:59], v[58:59], v[192:193]
	v_pk_mul_f32 v[54:55], v[54:55], v[196:197]
	v_pk_mul_f32 v[50:51], v[50:51], v[216:217]
	v_pk_mul_f32 v[48:49], v[48:49], v[214:215]
	v_pk_mul_f32 v[44:45], v[44:45], v[186:187]
	v_pk_mul_f32 v[40:41], v[40:41], v[190:191]
	v_pk_mul_f32 v[36:37], v[36:37], v[194:195]
	v_pk_mul_f32 v[46:47], v[46:47], v[188:189]
	v_pk_mul_f32 v[42:43], v[42:43], v[192:193]
	v_pk_mul_f32 v[38:39], v[38:39], v[196:197]
	v_pk_mul_f32 v[34:35], v[34:35], v[216:217]
	v_pk_mul_f32 v[32:33], v[32:33], v[214:215]
	v_pk_mul_f32 v[28:29], v[28:29], v[186:187]
	v_pk_mul_f32 v[24:25], v[24:25], v[190:191]
	v_pk_mul_f32 v[20:21], v[20:21], v[194:195]
	v_pk_mul_f32 v[30:31], v[30:31], v[188:189]
	v_pk_mul_f32 v[26:27], v[26:27], v[192:193]
	v_pk_mul_f32 v[22:23], v[22:23], v[196:197]
	v_pk_mul_f32 v[18:19], v[18:19], v[216:217]
	v_pk_mul_f32 v[16:17], v[16:17], v[214:215]
.LBB0_469:
	v_cndmask_b32_e64 v178, v169, v178, s[8:9]
	s_branch .Lafter_a1
.Lslow_a0:
	s_mov_b64 s[8:9], 0
	v_max_f32_e32 v90, v178, v248
	v_sub_f32_e32 v92, v178, v90
	v_mul_f32_e32 v92, 0x3dd53b94, v92
	v_exp_f32_e32 v92, v92
	s_nop 0
	v_cndmask_b32_e64 v179, v92, 1.0, s[8:9]
	v_cmp_gt_f32_e32 vcc, 1.0, v179
	s_cbranch_vccz .LBB0_463
	s_and_saveexec_b64 s[0:1], s[6:7]
	ds_write_b32 v205, v179 offset:128
	s_or_b64 exec, exec, s[0:1]
	s_waitcnt lgkmcnt(0)
	v_add_u32_e32 v91, s3, v184
	ds_read_b128 v[92:95], v91 offset:224
	ds_read_b128 v[188:191], v91 offset:192
	ds_read_b128 v[192:195], v91 offset:160
	ds_read_b128 v[214:217], v91 offset:128
	s_waitcnt lgkmcnt(3)
	v_pk_mul_f32 v[12:13], v[12:13], v[92:93]
	s_waitcnt lgkmcnt(2)
	v_pk_mul_f32 v[8:9], v[8:9], v[188:189]
	s_waitcnt lgkmcnt(1)
	v_pk_mul_f32 v[4:5], v[4:5], v[192:193]
	v_pk_mul_f32 v[14:15], v[14:15], v[94:95]
	v_pk_mul_f32 v[10:11], v[10:11], v[190:191]
	v_pk_mul_f32 v[6:7], v[6:7], v[194:195]
	s_waitcnt lgkmcnt(0)
	v_pk_mul_f32 v[2:3], v[2:3], v[216:217]
	v_pk_mul_f32 v[0:1], v[0:1], v[214:215]
	v_pk_mul_f32 v[60:61], v[60:61], v[92:93]
	v_pk_mul_f32 v[56:57], v[56:57], v[188:189]
	v_pk_mul_f32 v[52:53], v[52:53], v[192:193]
	v_pk_mul_f32 v[62:63], v[62:63], v[94:95]
	v_pk_mul_f32 v[58:59], v[58:59], v[190:191]
	v_pk_mul_f32 v[54:55], v[54:55], v[194:195]
	v_pk_mul_f32 v[50:51], v[50:51], v[216:217]
	v_pk_mul_f32 v[48:49], v[48:49], v[214:215]
	v_pk_mul_f32 v[44:45], v[44:45], v[92:93]
	v_pk_mul_f32 v[40:41], v[40:41], v[188:189]
	v_pk_mul_f32 v[36:37], v[36:37], v[192:193]
	v_pk_mul_f32 v[46:47], v[46:47], v[94:95]
	v_pk_mul_f32 v[42:43], v[42:43], v[190:191]
	v_pk_mul_f32 v[38:39], v[38:39], v[194:195]
	v_pk_mul_f32 v[34:35], v[34:35], v[216:217]
	v_pk_mul_f32 v[32:33], v[32:33], v[214:215]
	v_pk_mul_f32 v[28:29], v[28:29], v[92:93]
	v_pk_mul_f32 v[24:25], v[24:25], v[188:189]
	v_pk_mul_f32 v[20:21], v[20:21], v[192:193]
	v_pk_mul_f32 v[30:31], v[30:31], v[94:95]
	v_pk_mul_f32 v[26:27], v[26:27], v[190:191]
	v_pk_mul_f32 v[22:23], v[22:23], v[194:195]
	v_pk_mul_f32 v[18:19], v[18:19], v[216:217]
	v_pk_mul_f32 v[16:17], v[16:17], v[214:215]
